# gdn sample item: conv+silu step hand-written with all 33 input loads of a batch in flight (was a serialized exec-masked load chain); state-update pass prefetches the second 16 rows
# speedup vs baseline: 1.0321x; 1.0190x over previous
; DI float bf2f(bf16_t b) { return __uint_as_float(((unsigned)b) << 16); }
; DI float silu_f(float x) { return x * __builtin_amdgcn_rcpf(1.f + __expf(-x)); }
; DI void gdn_sample_item(const Params& p, int item, unsigned char* smem) {
;     ...
;     const int h = item & 7, b = item >> 3, tok0 = T_PR + b * 8;
; #pragma unroll
;     for (int m = 0; m < 6; ++m) {
;         const int e = tid + 512 * m, row = e / 384, c3 = e - row * 384, sec = c3 >> 7, col = sec * 1024 + h * 128 + (c3 & 127);
;         float o = 0.f;
; #pragma unroll
;         for (int j = 0; j < 4; ++j) { const int tr = row - 3 + j;
;             const float x = tr >= 0 ? bf2f(P0[(size_t)(tok0 + tr) * LDP0 + col]) : p.st_conv[(size_t)(b * 3 + (3 + tr)) * 3072 + col];
;             o += x * p.conv_w[j * 3072 + col]; }
;         raw[sec * 1024 + row * 128 + (c3 & 127)] = silu_f(o);
;     }
.LBB0_613:
	v_mov_b32_e32 v26, v1
	s_and_b32 s3, s20, 7
	s_lshl_b32 s23, s3, 7
	v_and_b32_e32 v41, 0x7f, v26
	s_and_b32 s4, s20, -8
	v_lshlrev_b32_e32 v42, 2, v41
	s_add_i32 s22, s4, 0x4000
	s_ashr_i32 s5, s20, 3
	s_mul_i32 s5, s5, 3
	v_or_b32_e32 v8, s23, v41
	s_add_u32 s98, s74, 0x3000
	s_addc_u32 s99, s75, 0
	s_add_u32 s12, s74, 0x6000
	s_addc_u32 s13, s75, 0
	s_add_u32 s6, s74, 0x9000
	s_addc_u32 s7, s75, 0
	v_mov_b32_e32 v43, v26
	v_mul_hi_u32 v44, v43, s29
	v_lshrrev_b32_e32 v44, 6, v44
	v_mul_u32_u24_e32 v49, 0x180, v44
	v_sub_u32_e32 v45, v43, v49
	v_lshlrev_b32_e32 v45, 3, v45
	v_and_b32_e32 v45, 0xfffffc00, v45
	v_or_b32_e32 v46, v45, v8
	v_lshlrev_b32_e32 v47, 2, v45
	v_lshl_add_u32 v47, v44, 9, v47
	v_add_u32_e32 v47, v47, v42
	v_lshlrev_b32_e32 v48, 2, v46
	v_add_u32_e32 v49, -3, v44
	v_max_i32_e32 v49, 0, v49
	v_add_u32_e32 v49, s22, v49
	v_mul_u32_u24_e32 v49, 0x2200, v49
	v_lshl_add_u32 v49, v46, 1, v49
	global_load_ushort v50, v49, s[86:87]
	global_load_dword v51, v48, s[74:75]
	v_add_u32_e32 v49, -2, v44
	v_max_i32_e32 v49, 0, v49
	v_add_u32_e32 v49, s22, v49
	v_mul_u32_u24_e32 v49, 0x2200, v49
	v_lshl_add_u32 v49, v46, 1, v49
	global_load_ushort v52, v49, s[86:87]
	global_load_dword v53, v48, s[98:99]
	v_add_u32_e32 v49, -1, v44
	v_max_i32_e32 v49, 0, v49
	v_add_u32_e32 v49, s22, v49
	v_mul_u32_u24_e32 v49, 0x2200, v49
	v_lshl_add_u32 v49, v46, 1, v49
	global_load_ushort v54, v49, s[86:87]
	global_load_dword v55, v48, s[12:13]
	v_add_u32_e32 v49, s22, v44
	v_mul_u32_u24_e32 v49, 0x2200, v49
	v_lshl_add_u32 v49, v46, 1, v49
	global_load_ushort v56, v49, s[86:87]
	global_load_dword v57, v48, s[6:7]
	v_cmp_gt_u32_e32 vcc, 3, v44
	s_and_saveexec_b64 s[0:1], vcc
	s_add_i32 s8, s5, 0
	v_add_u32_e32 v49, s8, v44
	v_mul_u32_u24_e32 v49, 0x3000, v49
	v_lshl_add_u32 v49, v46, 2, v49
	global_load_dword v58, v49, s[66:67]
	s_mov_b64 exec, s[0:1]
	v_cmp_gt_u32_e32 vcc, 2, v44
	s_and_saveexec_b64 s[0:1], vcc
	s_add_i32 s8, s5, 1
	v_add_u32_e32 v49, s8, v44
	v_mul_u32_u24_e32 v49, 0x3000, v49
	v_lshl_add_u32 v49, v46, 2, v49
	global_load_dword v59, v49, s[66:67]
	s_mov_b64 exec, s[0:1]
	v_cmp_gt_u32_e32 vcc, 1, v44
	s_and_saveexec_b64 s[0:1], vcc
	s_add_i32 s8, s5, 2
	v_add_u32_e32 v49, s8, v44
	v_mul_u32_u24_e32 v49, 0x3000, v49
	v_lshl_add_u32 v49, v46, 2, v49
	global_load_dword v60, v49, s[66:67]
	s_mov_b64 exec, s[0:1]
	v_add_u32_e32 v61, 0x200, v26
	v_mul_hi_u32 v62, v61, s29
	v_lshrrev_b32_e32 v62, 6, v62
	v_mul_u32_u24_e32 v67, 0x180, v62
	v_sub_u32_e32 v63, v61, v67
	v_lshlrev_b32_e32 v63, 3, v63
	v_and_b32_e32 v63, 0xfffffc00, v63
	v_or_b32_e32 v64, v63, v8
	v_lshlrev_b32_e32 v65, 2, v63
	v_lshl_add_u32 v65, v62, 9, v65
	v_add_u32_e32 v65, v65, v42
	v_lshlrev_b32_e32 v66, 2, v64
	v_add_u32_e32 v67, -3, v62
	v_max_i32_e32 v67, 0, v67
	v_add_u32_e32 v67, s22, v67
	v_mul_u32_u24_e32 v67, 0x2200, v67
	v_lshl_add_u32 v67, v64, 1, v67
	global_load_ushort v68, v67, s[86:87]
	global_load_dword v69, v66, s[74:75]
	v_add_u32_e32 v67, -2, v62
	v_max_i32_e32 v67, 0, v67
	v_add_u32_e32 v67, s22, v67
	v_mul_u32_u24_e32 v67, 0x2200, v67
	v_lshl_add_u32 v67, v64, 1, v67
	global_load_ushort v70, v67, s[86:87]
	global_load_dword v71, v66, s[98:99]
	v_add_u32_e32 v67, -1, v62
	v_max_i32_e32 v67, 0, v67
	v_add_u32_e32 v67, s22, v67
	v_mul_u32_u24_e32 v67, 0x2200, v67
	v_lshl_add_u32 v67, v64, 1, v67
	global_load_ushort v72, v67, s[86:87]
	global_load_dword v73, v66, s[12:13]
	v_add_u32_e32 v67, s22, v62
	v_mul_u32_u24_e32 v67, 0x2200, v67
	v_lshl_add_u32 v67, v64, 1, v67
	global_load_ushort v74, v67, s[86:87]
	global_load_dword v75, v66, s[6:7]
	v_cmp_gt_u32_e32 vcc, 3, v62
	s_and_saveexec_b64 s[0:1], vcc
	s_add_i32 s8, s5, 0
	v_add_u32_e32 v67, s8, v62
	v_mul_u32_u24_e32 v67, 0x3000, v67
	v_lshl_add_u32 v67, v64, 2, v67
	global_load_dword v76, v67, s[66:67]
	s_mov_b64 exec, s[0:1]
	v_cmp_gt_u32_e32 vcc, 2, v62
	s_and_saveexec_b64 s[0:1], vcc
	s_add_i32 s8, s5, 1
	v_add_u32_e32 v67, s8, v62
	v_mul_u32_u24_e32 v67, 0x3000, v67
	v_lshl_add_u32 v67, v64, 2, v67
	global_load_dword v77, v67, s[66:67]
	s_mov_b64 exec, s[0:1]
	v_cmp_gt_u32_e32 vcc, 1, v62
	s_and_saveexec_b64 s[0:1], vcc
	s_add_i32 s8, s5, 2
	v_add_u32_e32 v67, s8, v62
	v_mul_u32_u24_e32 v67, 0x3000, v67
	v_lshl_add_u32 v67, v64, 2, v67
	global_load_dword v78, v67, s[66:67]
	s_mov_b64 exec, s[0:1]
	v_add_u32_e32 v79, 0x400, v26
	v_mul_hi_u32 v80, v79, s29
	v_lshrrev_b32_e32 v80, 6, v80
	v_mul_u32_u24_e32 v85, 0x180, v80
	v_sub_u32_e32 v81, v79, v85
	v_lshlrev_b32_e32 v81, 3, v81
	v_and_b32_e32 v81, 0xfffffc00, v81
	v_or_b32_e32 v82, v81, v8
	v_lshlrev_b32_e32 v83, 2, v81
	v_lshl_add_u32 v83, v80, 9, v83
	v_add_u32_e32 v83, v83, v42
	v_lshlrev_b32_e32 v84, 2, v82
	v_add_u32_e32 v85, -3, v80
	v_max_i32_e32 v85, 0, v85
	v_add_u32_e32 v85, s22, v85
	v_mul_u32_u24_e32 v85, 0x2200, v85
	v_lshl_add_u32 v85, v82, 1, v85
	global_load_ushort v86, v85, s[86:87]
	global_load_dword v87, v84, s[74:75]
	v_add_u32_e32 v85, -2, v80
	v_max_i32_e32 v85, 0, v85
	v_add_u32_e32 v85, s22, v85
	v_mul_u32_u24_e32 v85, 0x2200, v85
	v_lshl_add_u32 v85, v82, 1, v85
	global_load_ushort v88, v85, s[86:87]
	global_load_dword v89, v84, s[98:99]
	v_add_u32_e32 v85, -1, v80
	v_max_i32_e32 v85, 0, v85
	v_add_u32_e32 v85, s22, v85
	v_mul_u32_u24_e32 v85, 0x2200, v85
	v_lshl_add_u32 v85, v82, 1, v85
	global_load_ushort v90, v85, s[86:87]
	global_load_dword v91, v84, s[12:13]
	v_add_u32_e32 v85, s22, v80
	v_mul_u32_u24_e32 v85, 0x2200, v85
	v_lshl_add_u32 v85, v82, 1, v85
	global_load_ushort v92, v85, s[86:87]
	global_load_dword v93, v84, s[6:7]
	v_cmp_gt_u32_e32 vcc, 3, v80
	s_and_saveexec_b64 s[0:1], vcc
	s_add_i32 s8, s5, 0
	v_add_u32_e32 v85, s8, v80
	v_mul_u32_u24_e32 v85, 0x3000, v85
	v_lshl_add_u32 v85, v82, 2, v85
	global_load_dword v94, v85, s[66:67]
	s_mov_b64 exec, s[0:1]
	v_cmp_gt_u32_e32 vcc, 2, v80
	s_and_saveexec_b64 s[0:1], vcc
	s_add_i32 s8, s5, 1
	v_add_u32_e32 v85, s8, v80
	v_mul_u32_u24_e32 v85, 0x3000, v85
	v_lshl_add_u32 v85, v82, 2, v85
	global_load_dword v95, v85, s[66:67]
	s_mov_b64 exec, s[0:1]
	v_cmp_gt_u32_e32 vcc, 1, v80
	s_and_saveexec_b64 s[0:1], vcc
	s_add_i32 s8, s5, 2
	v_add_u32_e32 v85, s8, v80
	v_mul_u32_u24_e32 v85, 0x3000, v85
	v_lshl_add_u32 v85, v82, 2, v85
	global_load_dword v96, v85, s[66:67]
	s_mov_b64 exec, s[0:1]
	s_waitcnt vmcnt(0)
; DI float bf2f(bf16_t b) { return __uint_as_float(((unsigned)b) << 16); }
; DI float silu_f(float x) { return x * __builtin_amdgcn_rcpf(1.f + __expf(-x)); }
; DI void gdn_sample_item(const Params& p, int item, unsigned char* smem) {
;     ...
;     for (int m = 0; m < 6; ++m) {
;         const int e = tid + 512 * m, row = e / 384, c3 = e - row * 384, sec = c3 >> 7, col = sec * 1024 + h * 128 + (c3 & 127);
;         float o = 0.f;
; #pragma unroll
;         for (int j = 0; j < 4; ++j) { const int tr = row - 3 + j;
;             const float x = tr >= 0 ? bf2f(P0[(size_t)(tok0 + tr) * LDP0 + col]) : p.st_conv[(size_t)(b * 3 + (3 + tr)) * 3072 + col];
;             o += x * p.conv_w[j * 3072 + col]; }
;         raw[sec * 1024 + row * 128 + (c3 & 127)] = silu_f(o);
;     }
	v_cmp_gt_u32_e32 vcc, 3, v44
	v_lshlrev_b32_e32 v50, 16, v50
	s_nop 1
	v_cndmask_b32_e32 v50, v50, v58, vcc
	v_cmp_gt_u32_e32 vcc, 2, v44
	v_lshlrev_b32_e32 v52, 16, v52
	s_nop 1
	v_cndmask_b32_e32 v52, v52, v59, vcc
	v_cmp_gt_u32_e32 vcc, 1, v44
	v_lshlrev_b32_e32 v54, 16, v54
	s_nop 1
	v_cndmask_b32_e32 v54, v54, v60, vcc
	v_lshlrev_b32_e32 v56, 16, v56
	v_mul_f32_e32 v49, v50, v51
	v_fmac_f32_e32 v49, v52, v53
	v_fmac_f32_e32 v49, v54, v55
	v_fmac_f32_e32 v49, v56, v57
	v_mul_f32_e32 v43, 0xbfb8aa3b, v49
	v_exp_f32_e32 v43, v43
	s_nop 0
	v_add_f32_e32 v43, 1.0, v43
	v_rcp_f32_e32 v43, v43
	s_nop 0
	v_mul_f32_e32 v49, v49, v43
	ds_write_b32 v47, v49
	v_cmp_gt_u32_e32 vcc, 3, v62
	v_lshlrev_b32_e32 v68, 16, v68
	s_nop 1
	v_cndmask_b32_e32 v68, v68, v76, vcc
	v_cmp_gt_u32_e32 vcc, 2, v62
	v_lshlrev_b32_e32 v70, 16, v70
	s_nop 1
	v_cndmask_b32_e32 v70, v70, v77, vcc
	v_cmp_gt_u32_e32 vcc, 1, v62
	v_lshlrev_b32_e32 v72, 16, v72
	s_nop 1
	v_cndmask_b32_e32 v72, v72, v78, vcc
	v_lshlrev_b32_e32 v74, 16, v74
	v_mul_f32_e32 v67, v68, v69
	v_fmac_f32_e32 v67, v70, v71
	v_fmac_f32_e32 v67, v72, v73
	v_fmac_f32_e32 v67, v74, v75
	v_mul_f32_e32 v61, 0xbfb8aa3b, v67
	v_exp_f32_e32 v61, v61
	s_nop 0
	v_add_f32_e32 v61, 1.0, v61
	v_rcp_f32_e32 v61, v61
	s_nop 0
	v_mul_f32_e32 v67, v67, v61
	ds_write_b32 v65, v67
	v_cmp_gt_u32_e32 vcc, 3, v80
	v_lshlrev_b32_e32 v86, 16, v86
	s_nop 1
	v_cndmask_b32_e32 v86, v86, v94, vcc
	v_cmp_gt_u32_e32 vcc, 2, v80
	v_lshlrev_b32_e32 v88, 16, v88
	s_nop 1
	v_cndmask_b32_e32 v88, v88, v95, vcc
	v_cmp_gt_u32_e32 vcc, 1, v80
	v_lshlrev_b32_e32 v90, 16, v90
	s_nop 1
	v_cndmask_b32_e32 v90, v90, v96, vcc
	v_lshlrev_b32_e32 v92, 16, v92
	v_mul_f32_e32 v85, v86, v87
	v_fmac_f32_e32 v85, v88, v89
	v_fmac_f32_e32 v85, v90, v91
	v_fmac_f32_e32 v85, v92, v93
	v_mul_f32_e32 v79, 0xbfb8aa3b, v85
	v_exp_f32_e32 v79, v79
	s_nop 0
	v_add_f32_e32 v79, 1.0, v79
	v_rcp_f32_e32 v79, v79
	s_nop 0
	v_mul_f32_e32 v85, v85, v79
	ds_write_b32 v83, v85
	v_add_u32_e32 v43, 0x600, v26
	v_mul_hi_u32 v44, v43, s29
	v_lshrrev_b32_e32 v44, 6, v44
	v_mul_u32_u24_e32 v49, 0x180, v44
	v_sub_u32_e32 v45, v43, v49
	v_lshlrev_b32_e32 v45, 3, v45
	v_and_b32_e32 v45, 0xfffffc00, v45
	v_or_b32_e32 v46, v45, v8
	v_lshlrev_b32_e32 v47, 2, v45
	v_lshl_add_u32 v47, v44, 9, v47
	v_add_u32_e32 v47, v47, v42
	v_lshlrev_b32_e32 v48, 2, v46
	v_add_u32_e32 v49, -3, v44
	v_max_i32_e32 v49, 0, v49
	v_add_u32_e32 v49, s22, v49
	v_mul_u32_u24_e32 v49, 0x2200, v49
	v_lshl_add_u32 v49, v46, 1, v49
	global_load_ushort v50, v49, s[86:87]
	global_load_dword v51, v48, s[74:75]
	v_add_u32_e32 v49, -2, v44
	v_max_i32_e32 v49, 0, v49
	v_add_u32_e32 v49, s22, v49
	v_mul_u32_u24_e32 v49, 0x2200, v49
	v_lshl_add_u32 v49, v46, 1, v49
	global_load_ushort v52, v49, s[86:87]
	global_load_dword v53, v48, s[98:99]
	v_add_u32_e32 v49, -1, v44
	v_max_i32_e32 v49, 0, v49
	v_add_u32_e32 v49, s22, v49
	v_mul_u32_u24_e32 v49, 0x2200, v49
	v_lshl_add_u32 v49, v46, 1, v49
	global_load_ushort v54, v49, s[86:87]
	global_load_dword v55, v48, s[12:13]
	v_add_u32_e32 v49, s22, v44
	v_mul_u32_u24_e32 v49, 0x2200, v49
	v_lshl_add_u32 v49, v46, 1, v49
	global_load_ushort v56, v49, s[86:87]
	global_load_dword v57, v48, s[6:7]
	v_cmp_gt_u32_e32 vcc, 3, v44
	s_and_saveexec_b64 s[0:1], vcc
	s_add_i32 s8, s5, 0
	v_add_u32_e32 v49, s8, v44
	v_mul_u32_u24_e32 v49, 0x3000, v49
	v_lshl_add_u32 v49, v46, 2, v49
	global_load_dword v58, v49, s[66:67]
	s_mov_b64 exec, s[0:1]
	v_cmp_gt_u32_e32 vcc, 2, v44
	s_and_saveexec_b64 s[0:1], vcc
	s_add_i32 s8, s5, 1
	v_add_u32_e32 v49, s8, v44
	v_mul_u32_u24_e32 v49, 0x3000, v49
	v_lshl_add_u32 v49, v46, 2, v49
	global_load_dword v59, v49, s[66:67]
	s_mov_b64 exec, s[0:1]
	v_cmp_gt_u32_e32 vcc, 1, v44
	s_and_saveexec_b64 s[0:1], vcc
	s_add_i32 s8, s5, 2
	v_add_u32_e32 v49, s8, v44
	v_mul_u32_u24_e32 v49, 0x3000, v49
	v_lshl_add_u32 v49, v46, 2, v49
	global_load_dword v60, v49, s[66:67]
	s_mov_b64 exec, s[0:1]
	v_add_u32_e32 v61, 0x800, v26
	v_mul_hi_u32 v62, v61, s29
	v_lshrrev_b32_e32 v62, 6, v62
	v_mul_u32_u24_e32 v67, 0x180, v62
	v_sub_u32_e32 v63, v61, v67
	v_lshlrev_b32_e32 v63, 3, v63
	v_and_b32_e32 v63, 0xfffffc00, v63
	v_or_b32_e32 v64, v63, v8
	v_lshlrev_b32_e32 v65, 2, v63
	v_lshl_add_u32 v65, v62, 9, v65
	v_add_u32_e32 v65, v65, v42
	v_lshlrev_b32_e32 v66, 2, v64
	v_add_u32_e32 v67, -3, v62
	v_max_i32_e32 v67, 0, v67
	v_add_u32_e32 v67, s22, v67
	v_mul_u32_u24_e32 v67, 0x2200, v67
	v_lshl_add_u32 v67, v64, 1, v67
	global_load_ushort v68, v67, s[86:87]
	global_load_dword v69, v66, s[74:75]
	v_add_u32_e32 v67, -2, v62
	v_max_i32_e32 v67, 0, v67
	v_add_u32_e32 v67, s22, v67
	v_mul_u32_u24_e32 v67, 0x2200, v67
	v_lshl_add_u32 v67, v64, 1, v67
	global_load_ushort v70, v67, s[86:87]
	global_load_dword v71, v66, s[98:99]
	v_add_u32_e32 v67, -1, v62
	v_max_i32_e32 v67, 0, v67
	v_add_u32_e32 v67, s22, v67
	v_mul_u32_u24_e32 v67, 0x2200, v67
	v_lshl_add_u32 v67, v64, 1, v67
	global_load_ushort v72, v67, s[86:87]
	global_load_dword v73, v66, s[12:13]
	v_add_u32_e32 v67, s22, v62
	v_mul_u32_u24_e32 v67, 0x2200, v67
	v_lshl_add_u32 v67, v64, 1, v67
	global_load_ushort v74, v67, s[86:87]
	global_load_dword v75, v66, s[6:7]
	v_cmp_gt_u32_e32 vcc, 3, v62
	s_and_saveexec_b64 s[0:1], vcc
	s_add_i32 s8, s5, 0
	v_add_u32_e32 v67, s8, v62
	v_mul_u32_u24_e32 v67, 0x3000, v67
	v_lshl_add_u32 v67, v64, 2, v67
	global_load_dword v76, v67, s[66:67]
	s_mov_b64 exec, s[0:1]
	v_cmp_gt_u32_e32 vcc, 2, v62
	s_and_saveexec_b64 s[0:1], vcc
	s_add_i32 s8, s5, 1
	v_add_u32_e32 v67, s8, v62
	v_mul_u32_u24_e32 v67, 0x3000, v67
	v_lshl_add_u32 v67, v64, 2, v67
	global_load_dword v77, v67, s[66:67]
; DI float bf2f(bf16_t b) { return __uint_as_float(((unsigned)b) << 16); }
; DI float silu_f(float x) { return x * __builtin_amdgcn_rcpf(1.f + __expf(-x)); }
; DI void gdn_sample_item(const Params& p, int item, unsigned char* smem) {
;     ...
;     for (int m = 0; m < 6; ++m) {
;         const int e = tid + 512 * m, row = e / 384, c3 = e - row * 384, sec = c3 >> 7, col = sec * 1024 + h * 128 + (c3 & 127);
;         float o = 0.f;
; #pragma unroll
;         for (int j = 0; j < 4; ++j) { const int tr = row - 3 + j;
;             const float x = tr >= 0 ? bf2f(P0[(size_t)(tok0 + tr) * LDP0 + col]) : p.st_conv[(size_t)(b * 3 + (3 + tr)) * 3072 + col];
;             o += x * p.conv_w[j * 3072 + col]; }
;         raw[sec * 1024 + row * 128 + (c3 & 127)] = silu_f(o);
;     }
;     if (tid < 8) {
;         const float braw = bf2f(P0[(size_t)(tok0 + tid) * LDP0 + 4096 + h]), araw = bf2f(P0[(size_t)(tok0 + tid) * LDP0 + 4104 + h]);
	s_mov_b64 exec, s[0:1]
	v_cmp_gt_u32_e32 vcc, 1, v62
	s_and_saveexec_b64 s[0:1], vcc
	s_add_i32 s8, s5, 2
	v_add_u32_e32 v67, s8, v62
	v_mul_u32_u24_e32 v67, 0x3000, v67
	v_lshl_add_u32 v67, v64, 2, v67
	global_load_dword v78, v67, s[66:67]
	s_mov_b64 exec, s[0:1]
	v_add_u32_e32 v79, 0xa00, v26
	v_mul_hi_u32 v80, v79, s29
	v_lshrrev_b32_e32 v80, 6, v80
	v_mul_u32_u24_e32 v85, 0x180, v80
	v_sub_u32_e32 v81, v79, v85
	v_lshlrev_b32_e32 v81, 3, v81
	v_and_b32_e32 v81, 0xfffffc00, v81
	v_or_b32_e32 v82, v81, v8
	v_lshlrev_b32_e32 v83, 2, v81
	v_lshl_add_u32 v83, v80, 9, v83
	v_add_u32_e32 v83, v83, v42
	v_lshlrev_b32_e32 v84, 2, v82
	v_add_u32_e32 v85, -3, v80
	v_max_i32_e32 v85, 0, v85
	v_add_u32_e32 v85, s22, v85
	v_mul_u32_u24_e32 v85, 0x2200, v85
	v_lshl_add_u32 v85, v82, 1, v85
	global_load_ushort v86, v85, s[86:87]
	global_load_dword v87, v84, s[74:75]
	v_add_u32_e32 v85, -2, v80
	v_max_i32_e32 v85, 0, v85
	v_add_u32_e32 v85, s22, v85
	v_mul_u32_u24_e32 v85, 0x2200, v85
	v_lshl_add_u32 v85, v82, 1, v85
	global_load_ushort v88, v85, s[86:87]
	global_load_dword v89, v84, s[98:99]
	v_add_u32_e32 v85, -1, v80
	v_max_i32_e32 v85, 0, v85
	v_add_u32_e32 v85, s22, v85
	v_mul_u32_u24_e32 v85, 0x2200, v85
	v_lshl_add_u32 v85, v82, 1, v85
	global_load_ushort v90, v85, s[86:87]
	global_load_dword v91, v84, s[12:13]
	v_add_u32_e32 v85, s22, v80
	v_mul_u32_u24_e32 v85, 0x2200, v85
	v_lshl_add_u32 v85, v82, 1, v85
	global_load_ushort v92, v85, s[86:87]
	global_load_dword v93, v84, s[6:7]
	v_cmp_gt_u32_e32 vcc, 3, v80
	s_and_saveexec_b64 s[0:1], vcc
	s_add_i32 s8, s5, 0
	v_add_u32_e32 v85, s8, v80
	v_mul_u32_u24_e32 v85, 0x3000, v85
	v_lshl_add_u32 v85, v82, 2, v85
	global_load_dword v94, v85, s[66:67]
	s_mov_b64 exec, s[0:1]
	v_cmp_gt_u32_e32 vcc, 2, v80
	s_and_saveexec_b64 s[0:1], vcc
	s_add_i32 s8, s5, 1
	v_add_u32_e32 v85, s8, v80
	v_mul_u32_u24_e32 v85, 0x3000, v85
	v_lshl_add_u32 v85, v82, 2, v85
	global_load_dword v95, v85, s[66:67]
	s_mov_b64 exec, s[0:1]
	v_cmp_gt_u32_e32 vcc, 1, v80
	s_and_saveexec_b64 s[0:1], vcc
	s_add_i32 s8, s5, 2
	v_add_u32_e32 v85, s8, v80
	v_mul_u32_u24_e32 v85, 0x3000, v85
	v_lshl_add_u32 v85, v82, 2, v85
	global_load_dword v96, v85, s[66:67]
	s_mov_b64 exec, s[0:1]
	s_waitcnt vmcnt(0)
	v_cmp_gt_u32_e32 vcc, 3, v44
	v_lshlrev_b32_e32 v50, 16, v50
	s_nop 1
	v_cndmask_b32_e32 v50, v50, v58, vcc
	v_cmp_gt_u32_e32 vcc, 2, v44
	v_lshlrev_b32_e32 v52, 16, v52
	s_nop 1
	v_cndmask_b32_e32 v52, v52, v59, vcc
	v_cmp_gt_u32_e32 vcc, 1, v44
	v_lshlrev_b32_e32 v54, 16, v54
	s_nop 1
	v_cndmask_b32_e32 v54, v54, v60, vcc
	v_lshlrev_b32_e32 v56, 16, v56
	v_mul_f32_e32 v49, v50, v51
	v_fmac_f32_e32 v49, v52, v53
	v_fmac_f32_e32 v49, v54, v55
	v_fmac_f32_e32 v49, v56, v57
	v_mul_f32_e32 v43, 0xbfb8aa3b, v49
	v_exp_f32_e32 v43, v43
	s_nop 0
	v_add_f32_e32 v43, 1.0, v43
	v_rcp_f32_e32 v43, v43
	s_nop 0
	v_mul_f32_e32 v49, v49, v43
	ds_write_b32 v47, v49
	v_cmp_gt_u32_e32 vcc, 3, v62
	v_lshlrev_b32_e32 v68, 16, v68
	s_nop 1
	v_cndmask_b32_e32 v68, v68, v76, vcc
	v_cmp_gt_u32_e32 vcc, 2, v62
	v_lshlrev_b32_e32 v70, 16, v70
	s_nop 1
	v_cndmask_b32_e32 v70, v70, v77, vcc
	v_cmp_gt_u32_e32 vcc, 1, v62
	v_lshlrev_b32_e32 v72, 16, v72
	s_nop 1
	v_cndmask_b32_e32 v72, v72, v78, vcc
	v_lshlrev_b32_e32 v74, 16, v74
	v_mul_f32_e32 v67, v68, v69
	v_fmac_f32_e32 v67, v70, v71
	v_fmac_f32_e32 v67, v72, v73
	v_fmac_f32_e32 v67, v74, v75
	v_mul_f32_e32 v61, 0xbfb8aa3b, v67
	v_exp_f32_e32 v61, v61
	s_nop 0
	v_add_f32_e32 v61, 1.0, v61
	v_rcp_f32_e32 v61, v61
	s_nop 0
	v_mul_f32_e32 v67, v67, v61
	ds_write_b32 v65, v67
	v_cmp_gt_u32_e32 vcc, 3, v80
	v_lshlrev_b32_e32 v86, 16, v86
	s_nop 1
	v_cndmask_b32_e32 v86, v86, v94, vcc
	v_cmp_gt_u32_e32 vcc, 2, v80
	v_lshlrev_b32_e32 v88, 16, v88
	s_nop 1
	v_cndmask_b32_e32 v88, v88, v95, vcc
	v_cmp_gt_u32_e32 vcc, 1, v80
	v_lshlrev_b32_e32 v90, 16, v90
	s_nop 1
	v_cndmask_b32_e32 v90, v90, v96, vcc
	v_lshlrev_b32_e32 v92, 16, v92
	v_mul_f32_e32 v85, v86, v87
	v_fmac_f32_e32 v85, v88, v89
	v_fmac_f32_e32 v85, v90, v91
	v_fmac_f32_e32 v85, v92, v93
	v_mul_f32_e32 v79, 0xbfb8aa3b, v85
	v_exp_f32_e32 v79, v79
	s_nop 0
	v_add_f32_e32 v79, 1.0, v79
	v_rcp_f32_e32 v79, v79
	s_nop 0
	v_mul_f32_e32 v85, v85, v79
	ds_write_b32 v83, v85
	v_cmp_gt_i32_e64 s[0:1], 8, v26
	s_and_saveexec_b64 s[4:5], s[0:1]
	s_cbranch_execz .LBB0_713
; DI float bf2f(bf16_t b) { return __uint_as_float(((unsigned)b) << 16); }
; DI void gdn_sample_item(const Params& p, int item, unsigned char* smem) {
;     ...
;     if (tid < 8) {
;         const float braw = bf2f(P0[(size_t)(tok0 + tid) * LDP0 + 4096 + h]), araw = bf2f(P0[(size_t)(tok0 + tid) * LDP0 + 4104 + h]);
;         const float xx = araw + p.dt_bias[h]; const float sp = xx > 20.f ? xx : log1pf(expf(xx));
;         Gs[16 + tid] = -expf(p.a_log[h]) * sp;
;         Gs[8 + tid] = 1.f / (1.f + expf(-braw));
;     }
	v_add_u32_e32 v4, s22, v26
	v_mov_b64_e32 v[2:3], s[86:87]
	v_mad_i64_i32 v[2:3], s[6:7], v4, s31, v[2:3]
	s_lshl_b32 s8, s3, 1
	v_lshl_add_u64 v[2:3], v[2:3], 0, s[8:9]
	v_add_co_u32_e32 v2, vcc, 0x2000, v2
	s_lshl_b32 s3, s3, 2
	s_nop 0
	v_addc_co_u32_e32 v3, vcc, 0, v3, vcc
	global_load_ushort v4, v[2:3], off offset:16
	v_readlane_b32 s36, v238, 2
	v_mov_b32_e32 v5, s3
	v_readlane_b32 s38, v238, 4
	v_readlane_b32 s39, v238, 5
	s_nop 4
	global_load_dword v5, v5, s[38:39]
	s_nop 0
	global_load_ushort v3, v[2:3], off
	s_mov_b32 s6, 0x41a00000
	v_readlane_b32 s37, v238, 3
	v_readlane_b32 s40, v238, 6
	v_readlane_b32 s41, v238, 7
	v_readlane_b32 s42, v238, 8
	v_readlane_b32 s43, v238, 9
	v_readlane_b32 s44, v238, 10
	v_readlane_b32 s45, v238, 11
	v_readlane_b32 s46, v238, 12
	v_readlane_b32 s47, v238, 13
	v_readlane_b32 s48, v238, 14
	v_readlane_b32 s49, v238, 15
	v_readlane_b32 s50, v238, 16
	v_readlane_b32 s51, v238, 17
	s_waitcnt vmcnt(0)
	v_lshlrev_b32_e32 v2, 16, v4
	v_add_f32_e32 v2, v5, v2
	v_cmp_nlt_f32_e32 vcc, s6, v2
	s_and_saveexec_b64 s[6:7], vcc
	s_cbranch_execz .LBB0_712
	v_mul_f32_e32 v4, 0x3fb8aa3b, v2
	v_rndne_f32_e32 v5, v4
	v_sub_f32_e32 v6, v4, v5
	v_fma_f32 v4, v2, s14, -v4
	v_fmac_f32_e32 v4, 0x32a5705f, v2
	v_add_f32_e32 v4, v6, v4
	v_cvt_i32_f32_e32 v5, v5
	v_exp_f32_e32 v4, v4
	v_cmp_ngt_f32_e32 vcc, s15, v2
	s_mov_b32 s8, 0x3f2aaaab
	v_ldexp_f32 v4, v4, v5
	v_cndmask_b32_e32 v4, 0, v4, vcc
	v_cmp_nlt_f32_e32 vcc, s16, v2
	s_nop 1
	v_cndmask_b32_e32 v2, v39, v4, vcc
	v_add_f32_e32 v6, 1.0, v2
	v_add_f32_e32 v4, -1.0, v6
	v_sub_f32_e32 v5, v4, v6
	v_add_f32_e32 v5, 1.0, v5
	v_sub_f32_e32 v4, v2, v4
	v_add_f32_e32 v7, v4, v5
	v_frexp_mant_f32_e32 v8, v6
	v_cvt_f64_f32_e32 v[4:5], v6
	v_frexp_exp_i32_f64_e32 v4, v[4:5]
	v_cmp_gt_f32_e32 vcc, s8, v8
	s_mov_b32 s8, 0x3f317218
	s_nop 0
	v_subbrev_co_u32_e32 v12, vcc, 0, v4, vcc
	v_sub_u32_e32 v4, 0, v12
	v_ldexp_f32 v5, v6, v4
	v_add_f32_e32 v6, -1.0, v5
	v_add_f32_e32 v8, 1.0, v5
	v_ldexp_f32 v4, v7, v4
	v_add_f32_e32 v7, 1.0, v6
	v_add_f32_e32 v9, -1.0, v8
	v_sub_f32_e32 v7, v5, v7
	v_sub_f32_e32 v5, v5, v9
	v_add_f32_e32 v7, v4, v7
	v_add_f32_e32 v4, v4, v5
	v_add_f32_e32 v13, v8, v4
	v_rcp_f32_e32 v15, v13
	v_sub_f32_e32 v5, v8, v13
	v_add_f32_e32 v14, v4, v5
	v_add_f32_e32 v5, v6, v7
	v_mul_f32_e32 v17, v5, v15
	v_sub_f32_e32 v4, v6, v5
	v_mul_f32_e32 v6, v13, v17
	v_fma_f32 v8, v17, v13, -v6
	v_fmac_f32_e32 v8, v17, v14
	v_add_f32_e32 v16, v7, v4
	v_add_f32_e32 v4, v6, v8
	v_sub_f32_e32 v7, v5, v4
	v_pk_add_f32 v[10:11], v[4:5], v[6:7] neg_lo:[0,1] neg_hi:[0,1]
	v_mov_b32_e32 v9, v4
	v_pk_add_f32 v[4:5], v[10:11], v[8:9] neg_lo:[0,1] neg_hi:[0,1]
	s_nop 0
	v_add_f32_e32 v5, v16, v5
	v_add_f32_e32 v4, v4, v5
	v_add_f32_e32 v5, v7, v4
	v_mul_f32_e32 v16, v15, v5
	v_mul_f32_e32 v6, v13, v16
	v_fma_f32 v8, v16, v13, -v6
	v_fmac_f32_e32 v8, v16, v14
	v_sub_f32_e32 v7, v7, v5
	v_add_f32_e32 v13, v4, v7
	v_add_f32_e32 v4, v6, v8
	v_sub_f32_e32 v7, v5, v4
	v_pk_add_f32 v[10:11], v[4:5], v[6:7] neg_lo:[0,1] neg_hi:[0,1]
	v_mov_b32_e32 v9, v4
	v_pk_add_f32 v[4:5], v[10:11], v[8:9] neg_lo:[0,1] neg_hi:[0,1]
	s_nop 0
	v_add_f32_e32 v5, v13, v5
	v_add_f32_e32 v4, v4, v5
	v_add_f32_e32 v5, v17, v16
	v_add_f32_e32 v4, v7, v4
	v_sub_f32_e32 v6, v5, v17
	v_mul_f32_e32 v4, v15, v4
	v_sub_f32_e32 v6, v16, v6
	v_add_f32_e32 v6, v6, v4
	v_add_f32_e32 v8, v5, v6
	v_mul_f32_e32 v9, v8, v8
	v_fmamk_f32 v4, v9, 0x3e9b6dac, v38
	v_fmaak_f32 v29, v9, v4, 0x3f2aaada
	v_cvt_f32_i32_e32 v4, v12
	v_sub_f32_e32 v5, v8, v5
	v_sub_f32_e32 v5, v6, v5
	v_ldexp_f32 v10, v5, 1
	v_mul_f32_e32 v5, v8, v9
	v_ldexp_f32 v7, v8, 1
	v_pk_mul_f32 v[8:9], v[4:5], v[28:29]
	s_nop 0
	v_fma_f32 v6, v4, s8, -v8
	v_fmac_f32_e32 v6, 0xb102e308, v4
	v_pk_add_f32 v[4:5], v[8:9], v[6:7]
	s_mov_b32 s8, 0x7f800000
	v_sub_f32_e32 v7, v5, v7
	v_sub_f32_e32 v7, v9, v7
	v_add_f32_e32 v11, v10, v7
	v_mov_b32_e32 v10, v8
	v_pk_add_f32 v[8:9], v[4:5], v[8:9] neg_lo:[0,1] neg_hi:[0,1]
	v_pk_add_f32 v[12:13], v[4:5], v[10:11]
	v_mov_b32_e32 v7, v4
	v_mov_b32_e32 v9, v13
	v_pk_add_f32 v[14:15], v[6:7], v[8:9] neg_lo:[0,1] neg_hi:[0,1]
	v_pk_add_f32 v[6:7], v[6:7], v[8:9]
	v_mov_b32_e32 v10, v11
	v_pk_add_f32 v[8:9], v[6:7], v[4:5] op_sel:[1,0] op_sel_hi:[0,1] neg_lo:[0,1] neg_hi:[0,1]
	v_pk_add_f32 v[16:17], v[12:13], v[8:9] op_sel_hi:[1,0] neg_lo:[0,1] neg_hi:[0,1]
	v_mov_b32_e32 v12, v13
	v_mov_b32_e32 v13, v7
	v_pk_mov_b32 v[8:9], v[4:5], v[8:9] op_sel:[1,0]
	v_mov_b32_e32 v11, v4
	v_pk_add_f32 v[8:9], v[12:13], v[8:9] neg_lo:[0,1] neg_hi:[0,1]
	v_mov_b32_e32 v16, v14
	v_pk_add_f32 v[4:5], v[10:11], v[8:9] neg_lo:[0,1] neg_hi:[0,1]
	v_mov_b32_e32 v15, v7
	v_pk_add_f32 v[8:9], v[16:17], v[4:5]
	v_cmp_neq_f32_e32 vcc, s8, v2
	v_pk_add_f32 v[10:11], v[8:9], v[8:9] op_sel:[0,1] op_sel_hi:[1,0]
	s_mov_b32 s8, 0x33800000
	v_pk_add_f32 v[6:7], v[6:7], v[10:11] op_sel:[1,0] op_sel_hi:[0,1]
	v_mov_b32_e32 v9, v6
	v_pk_add_f32 v[12:13], v[8:9], v[14:15] neg_lo:[0,1] neg_hi:[0,1]
	v_mov_b32_e32 v5, v10
	v_sub_f32_e32 v7, v8, v12
	v_pk_add_f32 v[4:5], v[4:5], v[12:13] neg_lo:[0,1] neg_hi:[0,1]
	v_sub_f32_e32 v7, v14, v7
	v_add_f32_e32 v4, v4, v7
	v_add_f32_e32 v4, v4, v5
	v_add_f32_e32 v4, v6, v4
	v_cndmask_b32_e32 v4, v39, v4, vcc
	v_cmp_lt_f32_e64 vcc, |v2|, s8
	s_nop 1
	v_cndmask_b32_e32 v2, v4, v2, vcc

; DI void gdn_sample_item(const Params& p, int item, unsigned char* smem) {
;     ...
;     { const float dl = Gs[24 + 7]; float* So = p.out + O_GSS + (size_t)item * 16384;
; #pragma unroll 1
;       for (int r0 = 0; r0 < 32; r0 += 16) {
;           float sv[16];
; #pragma unroll
;           for (int r = 0; r < 16; ++r) sv[r] = S0[(32 * qt + r0 + r) * 128 + dv];
; #pragma unroll
;           for (int r = 0; r < 16; ++r) { const int dk = 32 * qt + r0 + r; const f32x4 k0 = *(const f32x4*)(kdT + dk * 8), k1 = *(const f32x4*)(kdT + dk * 8 + 4);
;               So[dk * 128 + dv] = dl * sv[r] + k0.x * u[0] + k0.y * u[1] + k0.z * u[2] + k0.w * u[3] + k1.x * u[4] + k1.y * u[5] + k1.z * u[6] + k1.w * u[7]; }
.LBB0_829:
	v_or_b32_e32 v3, s3, v19
	v_lshl_or_b32 v16, v3, 7, v41
	v_or_b32_e32 v18, 1, v3
	v_or_b32_e32 v25, 2, v3
	v_or_b32_e32 v26, 3, v3
	v_or_b32_e32 v29, 4, v3
	v_or_b32_e32 v30, 5, v3
	v_or_b32_e32 v31, 6, v3
	v_or_b32_e32 v32, 7, v3
	v_or_b32_e32 v33, 8, v3
	v_or_b32_e32 v34, 9, v3
	v_or_b32_e32 v35, 10, v3
	v_or_b32_e32 v36, 11, v3
	v_or_b32_e32 v37, 12, v3
	v_or_b32_e32 v42, 13, v3
	v_or_b32_e32 v43, 14, v3
	v_or_b32_e32 v44, 15, v3
	v_lshl_add_u32 v3, v3, 5, 0
	v_ashrrev_i32_e32 v17, 31, v16
	v_lshl_or_b32 v24, v18, 7, v41
	v_lshl_or_b32 v150, v25, 7, v41
	v_lshl_or_b32 v160, v26, 7, v41
	v_lshl_or_b32 v162, v29, 7, v41
	v_lshl_or_b32 v164, v30, 7, v41
	v_lshl_or_b32 v166, v31, 7, v41
	v_lshl_or_b32 v168, v32, 7, v41
	v_lshl_or_b32 v170, v33, 7, v41
	v_lshl_or_b32 v172, v34, 7, v41
	v_lshl_or_b32 v174, v35, 7, v41
	v_lshl_or_b32 v176, v36, 7, v41
	v_lshl_or_b32 v178, v37, 7, v41
	v_lshl_or_b32 v180, v42, 7, v41
	v_lshl_or_b32 v182, v43, 7, v41
	v_lshl_or_b32 v184, v44, 7, v41
	ds_read_b128 v[12:15], v3 offset:20480
	ds_read_b128 v[20:23], v3 offset:20496
	v_lshl_add_u32 v3, v18, 5, 0
	v_lshl_add_u32 v18, v25, 5, 0
	v_lshlrev_b64 v[16:17], 2, v[16:17]
	v_ashrrev_i32_e32 v25, 31, v24
	v_ashrrev_i32_e32 v151, 31, v150
	v_ashrrev_i32_e32 v161, 31, v160
	v_ashrrev_i32_e32 v163, 31, v162
	v_ashrrev_i32_e32 v165, 31, v164
	v_ashrrev_i32_e32 v167, 31, v166
	v_lshl_add_u32 v70, v30, 5, 0
	v_lshl_add_u32 v78, v31, 5, 0
	v_lshl_add_u32 v86, v32, 5, 0
	v_lshl_add_u32 v94, v33, 5, 0
	v_lshl_add_u32 v102, v34, 5, 0
	v_lshl_add_u32 v110, v35, 5, 0
	v_lshl_add_u32 v118, v36, 5, 0
	v_lshl_add_u32 v126, v37, 5, 0
	v_lshl_add_u32 v134, v42, 5, 0
	v_lshl_add_u32 v142, v43, 5, 0
	v_ashrrev_i32_e32 v169, 31, v168
	v_ashrrev_i32_e32 v171, 31, v170
	v_ashrrev_i32_e32 v173, 31, v172
	v_ashrrev_i32_e32 v175, 31, v174
	v_ashrrev_i32_e32 v177, 31, v176
	v_ashrrev_i32_e32 v179, 31, v178
	v_ashrrev_i32_e32 v181, 31, v180
	v_ashrrev_i32_e32 v183, 31, v182
	v_ashrrev_i32_e32 v185, 31, v184
	v_lshl_add_u64 v[186:187], s[0:1], 0, v[16:17]
	v_lshlrev_b64 v[24:25], 2, v[24:25]
	v_lshlrev_b64 v[150:151], 2, v[150:151]
	v_lshlrev_b64 v[160:161], 2, v[160:161]
	v_lshlrev_b64 v[162:163], 2, v[162:163]
	v_lshlrev_b64 v[164:165], 2, v[164:165]
	v_lshlrev_b64 v[166:167], 2, v[166:167]
	v_lshl_add_u32 v26, v26, 5, 0
	v_lshl_add_u32 v29, v29, 5, 0
	v_lshl_add_u32 v154, v44, 5, 0
	ds_read_b128 v[30:33], v3 offset:20480
	ds_read_b128 v[34:37], v3 offset:20496
	ds_read_b128 v[42:45], v18 offset:20480
	ds_read_b128 v[46:49], v18 offset:20496
	ds_read_b128 v[50:53], v26 offset:20480
	ds_read_b128 v[54:57], v26 offset:20496
	ds_read_b128 v[58:61], v29 offset:20480
	ds_read_b128 v[62:65], v29 offset:20496
	ds_read_b128 v[66:69], v70 offset:20480
	ds_read_b128 v[70:73], v70 offset:20496
	ds_read_b128 v[74:77], v78 offset:20480
	ds_read_b128 v[78:81], v78 offset:20496
	ds_read_b128 v[82:85], v86 offset:20480
	ds_read_b128 v[86:89], v86 offset:20496
	ds_read_b128 v[90:93], v94 offset:20480
	ds_read_b128 v[94:97], v94 offset:20496
	ds_read_b128 v[98:101], v102 offset:20480
	ds_read_b128 v[102:105], v102 offset:20496
	ds_read_b128 v[106:109], v110 offset:20480
	ds_read_b128 v[110:113], v110 offset:20496
	ds_read_b128 v[114:117], v118 offset:20480
	ds_read_b128 v[118:121], v118 offset:20496
	ds_read_b128 v[122:125], v126 offset:20480
	ds_read_b128 v[126:129], v126 offset:20496
	ds_read_b128 v[130:133], v134 offset:20480
	ds_read_b128 v[134:137], v134 offset:20496
	ds_read_b128 v[138:141], v142 offset:20480
	ds_read_b128 v[142:145], v142 offset:20496
	ds_read_b128 v[146:149], v154 offset:20480
	ds_read_b128 v[156:159], v154 offset:20496
	v_lshlrev_b64 v[168:169], 2, v[168:169]
	v_lshlrev_b64 v[170:171], 2, v[170:171]
	v_lshlrev_b64 v[172:173], 2, v[172:173]
	v_lshlrev_b64 v[174:175], 2, v[174:175]
	v_lshlrev_b64 v[176:177], 2, v[176:177]
	v_lshlrev_b64 v[178:179], 2, v[178:179]
	v_lshlrev_b64 v[180:181], 2, v[180:181]
	v_lshlrev_b64 v[182:183], 2, v[182:183]
	v_lshlrev_b64 v[184:185], 2, v[184:185]
	s_cmp_lg_u32 s3, 0
	s_cbranch_scc1 .Lgs2_a
	global_load_dword v3, v[186:187], off
.Lgs2_a:
	v_lshl_add_u64 v[186:187], s[0:1], 0, v[24:25]
	v_lshl_add_u64 v[188:189], s[0:1], 0, v[150:151]
	v_lshl_add_u64 v[190:191], s[0:1], 0, v[160:161]
	v_lshl_add_u64 v[192:193], s[0:1], 0, v[162:163]
	v_lshl_add_u64 v[194:195], s[0:1], 0, v[164:165]
	v_lshl_add_u64 v[196:197], s[0:1], 0, v[166:167]
	v_lshl_add_u64 v[198:199], s[0:1], 0, v[168:169]
	v_lshl_add_u64 v[200:201], s[0:1], 0, v[170:171]
	v_lshl_add_u64 v[202:203], s[0:1], 0, v[172:173]
	v_lshl_add_u64 v[204:205], s[0:1], 0, v[174:175]
	v_lshl_add_u64 v[206:207], s[0:1], 0, v[176:177]
	v_lshl_add_u64 v[208:209], s[0:1], 0, v[178:179]
	v_lshl_add_u64 v[210:211], s[0:1], 0, v[180:181]
	v_lshl_add_u64 v[212:213], s[0:1], 0, v[182:183]
	v_lshl_add_u64 v[214:215], s[0:1], 0, v[184:185]
	s_cmp_lg_u32 s3, 0
	s_cbranch_scc1 .Lgs2_b
	global_load_dword v18, v[186:187], off
	global_load_dword v26, v[188:189], off
	global_load_dword v29, v[190:191], off
	global_load_dword v154, v[192:193], off
	s_nop 0
	global_load_dword v186, v[194:195], off
	global_load_dword v187, v[196:197], off
	global_load_dword v188, v[198:199], off
	global_load_dword v189, v[200:201], off
	global_load_dword v190, v[202:203], off
	global_load_dword v191, v[204:205], off
	global_load_dword v192, v[206:207], off
	global_load_dword v193, v[208:209], off
	global_load_dword v194, v[210:211], off
	global_load_dword v195, v[212:213], off
	global_load_dword v196, v[214:215], off
	s_add_u32 s98, s0, 0x2000
	s_addc_u32 s99, s1, 0
	global_load_dword v240, v16, s[98:99]
	global_load_dword v241, v24, s[98:99]
	global_load_dword v242, v150, s[98:99]
	global_load_dword v243, v160, s[98:99]
	global_load_dword v244, v162, s[98:99]
	global_load_dword v245, v164, s[98:99]
	global_load_dword v246, v166, s[98:99]
	global_load_dword v247, v168, s[98:99]
	global_load_dword v248, v170, s[98:99]
	global_load_dword v249, v172, s[98:99]
	global_load_dword v250, v174, s[98:99]
	global_load_dword v251, v176, s[98:99]
	global_load_dword v252, v178, s[98:99]
	global_load_dword v253, v180, s[98:99]
	global_load_dword v254, v182, s[98:99]
	global_load_dword v255, v184, s[98:99]
	s_branch .Lgs2_c
; DI void gdn_sample_item(const Params& p, int item, unsigned char* smem) {
;     ...
;           float sv[16];
; #pragma unroll
;           for (int r = 0; r < 16; ++r) sv[r] = S0[(32 * qt + r0 + r) * 128 + dv];
; #pragma unroll
;           for (int r = 0; r < 16; ++r) { const int dk = 32 * qt + r0 + r; const f32x4 k0 = *(const f32x4*)(kdT + dk * 8), k1 = *(const f32x4*)(kdT + dk * 8 + 4);
;               So[dk * 128 + dv] = dl * sv[r] + k0.x * u[0] + k0.y * u[1] + k0.z * u[2] + k0.w * u[3] + k1.x * u[4] + k1.y * u[5] + k1.z * u[6] + k1.w * u[7]; }
;       } }
.Lgs2_b:
	s_waitcnt vmcnt(16)
	v_mov_b32_e32 v3, v240
	v_mov_b32_e32 v18, v241
	v_mov_b32_e32 v26, v242
	v_mov_b32_e32 v29, v243
	v_mov_b32_e32 v154, v244
	v_mov_b32_e32 v186, v245
	v_mov_b32_e32 v187, v246
	v_mov_b32_e32 v188, v247
	v_mov_b32_e32 v189, v248
	v_mov_b32_e32 v190, v249
	v_mov_b32_e32 v191, v250
	v_mov_b32_e32 v192, v251
	v_mov_b32_e32 v193, v252
	v_mov_b32_e32 v194, v253
	v_mov_b32_e32 v195, v254
	v_mov_b32_e32 v196, v255
.Lgs2_c:
	s_waitcnt lgkmcnt(14)
	v_mul_f32_e32 v12, v4, v12
	v_mul_f32_e32 v30, v4, v30
	v_mul_f32_e32 v42, v4, v42
	v_mul_f32_e32 v50, v4, v50
	v_mul_f32_e32 v58, v4, v58
	v_mul_f32_e32 v66, v4, v66
	v_mul_f32_e32 v74, v4, v74
	v_mul_f32_e32 v82, v4, v82
	v_mul_f32_e32 v90, v4, v90
	s_waitcnt lgkmcnt(13)
	v_mul_f32_e32 v98, v4, v98
	s_waitcnt lgkmcnt(11)
	v_mul_f32_e32 v106, v4, v106
	s_waitcnt lgkmcnt(9)
	v_mul_f32_e32 v114, v4, v114
	s_waitcnt lgkmcnt(7)
	v_mul_f32_e32 v122, v4, v122
	s_waitcnt lgkmcnt(5)
	v_mul_f32_e32 v130, v4, v130
	s_waitcnt lgkmcnt(3)
	v_mul_f32_e32 v138, v4, v138
	s_waitcnt lgkmcnt(1)
	v_mul_f32_e32 v146, v4, v146
	s_mov_b32 s3, 16
	s_and_b64 vcc, exec, s[6:7]
	s_mov_b64 s[6:7], 0
	v_lshl_add_u64 v[16:17], s[4:5], 0, v[16:17]
	v_lshl_add_u64 v[24:25], s[4:5], 0, v[24:25]
	v_lshl_add_u64 v[150:151], s[4:5], 0, v[150:151]
	v_lshl_add_u64 v[160:161], s[4:5], 0, v[160:161]
	v_lshl_add_u64 v[162:163], s[4:5], 0, v[162:163]
	v_lshl_add_u64 v[164:165], s[4:5], 0, v[164:165]
	v_lshl_add_u64 v[166:167], s[4:5], 0, v[166:167]
	v_lshl_add_u64 v[168:169], s[4:5], 0, v[168:169]
	v_lshl_add_u64 v[170:171], s[4:5], 0, v[170:171]
	v_lshl_add_u64 v[172:173], s[4:5], 0, v[172:173]
	v_lshl_add_u64 v[174:175], s[4:5], 0, v[174:175]
	v_lshl_add_u64 v[176:177], s[4:5], 0, v[176:177]
	v_lshl_add_u64 v[178:179], s[4:5], 0, v[178:179]
	v_lshl_add_u64 v[180:181], s[4:5], 0, v[180:181]
	v_lshl_add_u64 v[182:183], s[4:5], 0, v[182:183]
	v_lshl_add_u64 v[184:185], s[4:5], 0, v[184:185]
	s_waitcnt vmcnt(31)
	v_fmac_f32_e32 v12, v2, v3
	v_fmac_f32_e32 v12, v5, v13
	s_waitcnt vmcnt(30)
	v_fmac_f32_e32 v30, v2, v18
	s_waitcnt vmcnt(29)
	v_fmac_f32_e32 v42, v2, v26
	s_waitcnt vmcnt(28)
	v_fmac_f32_e32 v50, v2, v29
	s_waitcnt vmcnt(27)
	v_fmac_f32_e32 v58, v2, v154
	s_waitcnt vmcnt(26)
	v_fmac_f32_e32 v66, v2, v186
	s_waitcnt vmcnt(25)
	v_fmac_f32_e32 v74, v2, v187
	s_waitcnt vmcnt(24)
	v_fmac_f32_e32 v82, v2, v188
	s_waitcnt vmcnt(23)
	v_fmac_f32_e32 v90, v2, v189
	s_waitcnt vmcnt(22)
	v_fmac_f32_e32 v98, v2, v190
	s_waitcnt vmcnt(21)
	v_fmac_f32_e32 v106, v2, v191
	s_waitcnt vmcnt(20)
	v_fmac_f32_e32 v114, v2, v192
	s_waitcnt vmcnt(19)
	v_fmac_f32_e32 v122, v2, v193
	s_waitcnt vmcnt(18)
	v_fmac_f32_e32 v130, v2, v194
	s_waitcnt vmcnt(17)
	v_fmac_f32_e32 v138, v2, v195
	s_waitcnt vmcnt(16)
	v_fmac_f32_e32 v146, v2, v196
	v_fmac_f32_e32 v30, v5, v31
	v_fmac_f32_e32 v12, v6, v14
	v_fmac_f32_e32 v42, v5, v43
	v_fmac_f32_e32 v50, v5, v51
	v_fmac_f32_e32 v58, v5, v59
	v_fmac_f32_e32 v66, v5, v67
	v_fmac_f32_e32 v74, v5, v75
	v_fmac_f32_e32 v82, v5, v83
	v_fmac_f32_e32 v90, v5, v91
	v_fmac_f32_e32 v98, v5, v99
	v_fmac_f32_e32 v106, v5, v107
	v_fmac_f32_e32 v114, v5, v115
	v_fmac_f32_e32 v122, v5, v123
	v_fmac_f32_e32 v130, v5, v131
	v_fmac_f32_e32 v138, v5, v139
	v_fmac_f32_e32 v146, v5, v147
	v_fmac_f32_e32 v30, v6, v32
	v_fmac_f32_e32 v12, v7, v15
	v_fmac_f32_e32 v42, v6, v44
	v_fmac_f32_e32 v50, v6, v52
	v_fmac_f32_e32 v58, v6, v60
	v_fmac_f32_e32 v66, v6, v68
	v_fmac_f32_e32 v74, v6, v76
	v_fmac_f32_e32 v82, v6, v84
	v_fmac_f32_e32 v90, v6, v92
	v_fmac_f32_e32 v98, v6, v100
	v_fmac_f32_e32 v106, v6, v108
	v_fmac_f32_e32 v114, v6, v116
	v_fmac_f32_e32 v122, v6, v124
	v_fmac_f32_e32 v130, v6, v132
	v_fmac_f32_e32 v138, v6, v140
	v_fmac_f32_e32 v146, v6, v148
	v_fmac_f32_e32 v30, v7, v33
	v_fmac_f32_e32 v12, v8, v20
	v_fmac_f32_e32 v42, v7, v45
	v_fmac_f32_e32 v50, v7, v53
	v_fmac_f32_e32 v58, v7, v61
	v_fmac_f32_e32 v66, v7, v69
	v_fmac_f32_e32 v74, v7, v77
	v_fmac_f32_e32 v82, v7, v85
	v_fmac_f32_e32 v90, v7, v93
	v_fmac_f32_e32 v98, v7, v101
	v_fmac_f32_e32 v106, v7, v109
	v_fmac_f32_e32 v114, v7, v117
	v_fmac_f32_e32 v122, v7, v125
	v_fmac_f32_e32 v130, v7, v133
	v_fmac_f32_e32 v138, v7, v141
	v_fmac_f32_e32 v146, v7, v149
	v_fmac_f32_e32 v30, v8, v34
	v_fmac_f32_e32 v12, v9, v21
	v_fmac_f32_e32 v42, v8, v46
	v_fmac_f32_e32 v50, v8, v54
	v_fmac_f32_e32 v58, v8, v62
	v_fmac_f32_e32 v66, v8, v70
	v_fmac_f32_e32 v74, v8, v78
	v_fmac_f32_e32 v82, v8, v86
	v_fmac_f32_e32 v90, v8, v94
	v_fmac_f32_e32 v98, v8, v102
	v_fmac_f32_e32 v106, v8, v110
	v_fmac_f32_e32 v114, v8, v118
	v_fmac_f32_e32 v122, v8, v126
	v_fmac_f32_e32 v130, v8, v134
	v_fmac_f32_e32 v138, v8, v142
	s_waitcnt lgkmcnt(0)
	v_fmac_f32_e32 v146, v8, v156
	v_fmac_f32_e32 v30, v9, v35
	v_fmac_f32_e32 v12, v10, v22
	v_fmac_f32_e32 v42, v9, v47
	v_fmac_f32_e32 v50, v9, v55
	v_fmac_f32_e32 v58, v9, v63
	v_fmac_f32_e32 v66, v9, v71
	v_fmac_f32_e32 v74, v9, v79
	v_fmac_f32_e32 v82, v9, v87
	v_fmac_f32_e32 v90, v9, v95
	v_fmac_f32_e32 v98, v9, v103
	v_fmac_f32_e32 v106, v9, v111
	v_fmac_f32_e32 v114, v9, v119
	v_fmac_f32_e32 v122, v9, v127
	v_fmac_f32_e32 v130, v9, v135
	v_fmac_f32_e32 v138, v9, v143
	v_fmac_f32_e32 v146, v9, v157
	v_fmac_f32_e32 v30, v10, v36
	v_fmac_f32_e32 v12, v11, v23
	v_fmac_f32_e32 v42, v10, v48
	v_fmac_f32_e32 v50, v10, v56
	v_fmac_f32_e32 v58, v10, v64
	v_fmac_f32_e32 v66, v10, v72
	v_fmac_f32_e32 v74, v10, v80
	v_fmac_f32_e32 v82, v10, v88
	v_fmac_f32_e32 v90, v10, v96
	v_fmac_f32_e32 v98, v10, v104
	v_fmac_f32_e32 v106, v10, v112
	v_fmac_f32_e32 v114, v10, v120
	v_fmac_f32_e32 v122, v10, v128
	v_fmac_f32_e32 v130, v10, v136
	v_fmac_f32_e32 v138, v10, v144
	v_fmac_f32_e32 v146, v10, v158
	v_fmac_f32_e32 v30, v11, v37
	global_store_dword v[16:17], v12, off
	v_fmac_f32_e32 v42, v11, v49
	v_fmac_f32_e32 v50, v11, v57
	v_fmac_f32_e32 v58, v11, v65
	v_fmac_f32_e32 v66, v11, v73
	v_fmac_f32_e32 v74, v11, v81
	v_fmac_f32_e32 v82, v11, v89
	v_fmac_f32_e32 v90, v11, v97
	v_fmac_f32_e32 v98, v11, v105
	v_fmac_f32_e32 v106, v11, v113
	v_fmac_f32_e32 v114, v11, v121
	v_fmac_f32_e32 v122, v11, v129
	v_fmac_f32_e32 v130, v11, v137
	v_fmac_f32_e32 v138, v11, v145
	v_fmac_f32_e32 v146, v11, v159
	global_store_dword v[24:25], v30, off
	global_store_dword v[150:151], v42, off
	global_store_dword v[160:161], v50, off
	global_store_dword v[162:163], v58, off
	global_store_dword v[164:165], v66, off
	global_store_dword v[166:167], v74, off
	global_store_dword v[168:169], v82, off
	global_store_dword v[170:171], v90, off
	global_store_dword v[172:173], v98, off
	global_store_dword v[174:175], v106, off
	global_store_dword v[176:177], v114, off
	global_store_dword v[178:179], v122, off
	global_store_dword v[180:181], v130, off
	global_store_dword v[182:183], v138, off
	global_store_dword v[184:185], v146, off
	s_cbranch_vccnz .LBB0_829
	s_waitcnt lgkmcnt(0)
	s_barrier
	v_readlane_b32 s0, v238, 31
	s_add_i32 s20, s0, s20
	s_cmpk_lt_i32 s20, 0x400
	s_cbranch_scc1 .LBB0_613

; __global__ void __launch_bounds__(512) hybrid_fwd(Params p) {
	.amdhsa_kernel _Z10hybrid_fwd6Params
		.amdhsa_group_segment_fixed_size 0
		.amdhsa_private_segment_fixed_size 0
		.amdhsa_kernarg_size 416
		.amdhsa_user_sgpr_count 2
		.amdhsa_user_sgpr_dispatch_ptr 0
		.amdhsa_user_sgpr_queue_ptr 0
		.amdhsa_user_sgpr_kernarg_segment_ptr 1
		.amdhsa_user_sgpr_dispatch_id 0
		.amdhsa_user_sgpr_kernarg_preload_length 0
		.amdhsa_user_sgpr_kernarg_preload_offset 0
		.amdhsa_user_sgpr_private_segment_size 0
		.amdhsa_uses_dynamic_stack 0
		.amdhsa_enable_private_segment 0
		.amdhsa_system_sgpr_workgroup_id_x 1
		.amdhsa_system_sgpr_workgroup_id_y 0
		.amdhsa_system_sgpr_workgroup_id_z 0
		.amdhsa_system_sgpr_workgroup_info 0
		.amdhsa_system_vgpr_workitem_id 2
		.amdhsa_next_free_vgpr 256
		.amdhsa_next_free_sgpr 102
		.amdhsa_accum_offset 256
		.amdhsa_reserve_vcc 1
		.amdhsa_float_round_mode_32 0
		.amdhsa_float_round_mode_16_64 0
		.amdhsa_float_denorm_mode_32 3
		.amdhsa_float_denorm_mode_16_64 3
		.amdhsa_dx10_clamp 1
		.amdhsa_ieee_mode 1
		.amdhsa_fp16_overflow 0
		.amdhsa_tg_split 0
		.amdhsa_exception_fp_ieee_invalid_op 0
		.amdhsa_exception_fp_denorm_src 0
		.amdhsa_exception_fp_ieee_div_zero 0
		.amdhsa_exception_fp_ieee_overflow 0
		.amdhsa_exception_fp_ieee_underflow 0
		.amdhsa_exception_fp_ieee_inexact 0
		.amdhsa_exception_int_div_zero 0
	.end_amdhsa_kernel

; __global__ void __launch_bounds__(512) hybrid_fwd(Params p) {
amdhsa.kernels:
  - .agpr_count:     0
    .args:
      - .offset:         0
        .size:           160
        .value_kind:     by_value
      - .offset:         160
        .size:           4
        .value_kind:     hidden_block_count_x
      - .offset:         164
        .size:           4
        .value_kind:     hidden_block_count_y
      - .offset:         168
        .size:           4
        .value_kind:     hidden_block_count_z
      - .offset:         172
        .size:           2
        .value_kind:     hidden_group_size_x
      - .offset:         174
        .size:           2
        .value_kind:     hidden_group_size_y
      - .offset:         176
        .size:           2
        .value_kind:     hidden_group_size_z
      - .offset:         178
        .size:           2
        .value_kind:     hidden_remainder_x
      - .offset:         180
        .size:           2
        .value_kind:     hidden_remainder_y
      - .offset:         182
        .size:           2
        .value_kind:     hidden_remainder_z
      - .offset:         200
        .size:           8
        .value_kind:     hidden_global_offset_x
      - .offset:         208
        .size:           8
        .value_kind:     hidden_global_offset_y
      - .offset:         216
        .size:           8
        .value_kind:     hidden_global_offset_z
      - .offset:         224
        .size:           2
        .value_kind:     hidden_grid_dims
      - .offset:         248
        .size:           8
        .value_kind:     hidden_multigrid_sync_arg
      - .offset:         280
        .size:           4
        .value_kind:     hidden_dynamic_lds_size
    .group_segment_fixed_size: 0
    .kernarg_segment_align: 8
    .kernarg_segment_size: 416
    .language:       OpenCL C
    .language_version:
      - 2
      - 0
    .max_flat_workgroup_size: 512
    .name:           _Z10hybrid_fwd6Params
    .private_segment_fixed_size: 0
    .sgpr_count:     108
    .sgpr_spill_count: 37
    .symbol:         _Z10hybrid_fwd6Params.kd
    .uniform_work_group_size: 1
    .uses_dynamic_stack: false
    .vgpr_count:     256
    .vgpr_spill_count: 0
    .wavefront_size: 64
